# split-K pair: 34 / 30 K-tiles so the partial is ready when the K-lo CU finishes; partial add keeps 16 loads in flight throughout
# speedup vs baseline: 1.0018x; 1.0018x over previous
.Lp9_stage_b:
	s_mov_b32 s100, 10
	s_movk_i32 s91, 30
	s_movk_i32 s97, 31
	s_cmpk_lt_u32 s101, 0x80
	s_cbranch_scc0 .Lp9_hi
	s_mov_b32 s96, 1
	s_add_u32 s4, s78, 0x8000000
	s_addc_u32 s5, s79, 0
	s_add_i32 s98, s101, 0x200
	s_movk_i32 s99, 0x280
	s_branch .Lp9_body
.Lp9_hi:
	s_mov_b32 s96, 2
	s_movk_i32 s91, 26
	s_movk_i32 s97, 27
	s_add_u32 s4, s78, 0x8001100
	s_addc_u32 s5, s79, 0
	s_add_u32 s74, s74, 0x1100
	s_addc_u32 s75, s75, 0
	s_add_i32 s98, s101, 0x180
	s_movk_i32 s99, 0x280
	s_branch .Lp9_body

.Lp9_lo_pd:
	s_or_b64 exec, exec, s[84:85]
	s_barrier
	buffer_inv sc1
	s_lshl_b32 s86, s32, 18
	s_add_u32 s86, s86, 0x1c000000
	s_add_u32 s86, s78, s86
	s_addc_u32 s87, s79, 0
	v_lshlrev_b32_e32 v80, 4, v210
	global_load_dwordx4 v[170:173], v80, s[86:87]
	s_add_u32 s86, s86, 0x2000
	s_addc_u32 s87, s87, 0
	global_load_dwordx4 v[174:177], v80, s[86:87]
	s_add_u32 s86, s86, 0x2000
	s_addc_u32 s87, s87, 0
	global_load_dwordx4 v[178:181], v80, s[86:87]
	s_add_u32 s86, s86, 0x2000
	s_addc_u32 s87, s87, 0
	global_load_dwordx4 v[182:185], v80, s[86:87]
	s_add_u32 s86, s86, 0x2000
	s_addc_u32 s87, s87, 0
	global_load_dwordx4 v[186:189], v80, s[86:87]
	s_add_u32 s86, s86, 0x2000
	s_addc_u32 s87, s87, 0
	global_load_dwordx4 v[190:193], v80, s[86:87]
	s_add_u32 s86, s86, 0x2000
	s_addc_u32 s87, s87, 0
	global_load_dwordx4 v[194:197], v80, s[86:87]
	s_add_u32 s86, s86, 0x2000
	s_addc_u32 s87, s87, 0
	global_load_dwordx4 v[198:201], v80, s[86:87]
	s_add_u32 s86, s86, 0x2000
	s_addc_u32 s87, s87, 0
	global_load_dwordx4 v[202:205], v80, s[86:87]
	s_add_u32 s86, s86, 0x2000
	s_addc_u32 s87, s87, 0
	global_load_dwordx4 v[206:209], v80, s[86:87]
	s_add_u32 s86, s86, 0x2000
	s_addc_u32 s87, s87, 0
	global_load_dwordx4 v[216:219], v80, s[86:87]
	s_add_u32 s86, s86, 0x2000
	s_addc_u32 s87, s87, 0
	global_load_dwordx4 v[220:223], v80, s[86:87]
	s_add_u32 s86, s86, 0x2000
	s_addc_u32 s87, s87, 0
	global_load_dwordx4 v[224:227], v80, s[86:87]
	s_add_u32 s86, s86, 0x2000
	s_addc_u32 s87, s87, 0
	global_load_dwordx4 v[84:87], v80, s[86:87]
	s_add_u32 s86, s86, 0x2000
	s_addc_u32 s87, s87, 0
	global_load_dwordx4 v[88:91], v80, s[86:87]
	s_add_u32 s86, s86, 0x2000
	s_addc_u32 s87, s87, 0
	global_load_dwordx4 v[92:95], v80, s[86:87]
	s_add_u32 s86, s86, 0x2000
	s_addc_u32 s87, s87, 0
	s_waitcnt vmcnt(15)
	v_pk_add_f32 v[0:1], v[0:1], v[170:171]
	v_pk_add_f32 v[2:3], v[2:3], v[172:173]
	global_load_dwordx4 v[170:173], v80, s[86:87]
	s_add_u32 s86, s86, 0x2000
	s_addc_u32 s87, s87, 0
	s_waitcnt vmcnt(15)
	v_pk_add_f32 v[4:5], v[4:5], v[174:175]
	v_pk_add_f32 v[6:7], v[6:7], v[176:177]
	global_load_dwordx4 v[174:177], v80, s[86:87]
	s_add_u32 s86, s86, 0x2000
	s_addc_u32 s87, s87, 0
	s_waitcnt vmcnt(15)
	v_pk_add_f32 v[8:9], v[8:9], v[178:179]
	v_pk_add_f32 v[10:11], v[10:11], v[180:181]
	global_load_dwordx4 v[178:181], v80, s[86:87]
	s_add_u32 s86, s86, 0x2000
	s_addc_u32 s87, s87, 0
	s_waitcnt vmcnt(15)
	v_pk_add_f32 v[12:13], v[12:13], v[182:183]
	v_pk_add_f32 v[14:15], v[14:15], v[184:185]
	global_load_dwordx4 v[182:185], v80, s[86:87]
	s_add_u32 s86, s86, 0x2000
	s_addc_u32 s87, s87, 0
	s_waitcnt vmcnt(15)
	v_pk_add_f32 v[16:17], v[16:17], v[186:187]
	v_pk_add_f32 v[18:19], v[18:19], v[188:189]
	global_load_dwordx4 v[186:189], v80, s[86:87]
	s_add_u32 s86, s86, 0x2000
	s_addc_u32 s87, s87, 0
	s_waitcnt vmcnt(15)
	v_pk_add_f32 v[20:21], v[20:21], v[190:191]
	v_pk_add_f32 v[22:23], v[22:23], v[192:193]
	global_load_dwordx4 v[190:193], v80, s[86:87]
	s_add_u32 s86, s86, 0x2000
	s_addc_u32 s87, s87, 0
	s_waitcnt vmcnt(15)
	v_pk_add_f32 v[24:25], v[24:25], v[194:195]
	v_pk_add_f32 v[26:27], v[26:27], v[196:197]
	global_load_dwordx4 v[194:197], v80, s[86:87]
	s_add_u32 s86, s86, 0x2000
	s_addc_u32 s87, s87, 0
	s_waitcnt vmcnt(15)
	v_pk_add_f32 v[28:29], v[28:29], v[198:199]
	v_pk_add_f32 v[30:31], v[30:31], v[200:201]
	global_load_dwordx4 v[198:201], v80, s[86:87]
	s_add_u32 s86, s86, 0x2000
	s_addc_u32 s87, s87, 0
	s_waitcnt vmcnt(15)
	v_pk_add_f32 v[32:33], v[32:33], v[202:203]
	v_pk_add_f32 v[34:35], v[34:35], v[204:205]
	global_load_dwordx4 v[202:205], v80, s[86:87]
	s_add_u32 s86, s86, 0x2000
	s_addc_u32 s87, s87, 0
	s_waitcnt vmcnt(15)
	v_pk_add_f32 v[36:37], v[36:37], v[206:207]
	v_pk_add_f32 v[38:39], v[38:39], v[208:209]
	global_load_dwordx4 v[206:209], v80, s[86:87]
	s_add_u32 s86, s86, 0x2000
	s_addc_u32 s87, s87, 0
	s_waitcnt vmcnt(15)
	v_pk_add_f32 v[40:41], v[40:41], v[216:217]
	v_pk_add_f32 v[42:43], v[42:43], v[218:219]
	global_load_dwordx4 v[216:219], v80, s[86:87]
	s_add_u32 s86, s86, 0x2000
	s_addc_u32 s87, s87, 0
	s_waitcnt vmcnt(15)
	v_pk_add_f32 v[44:45], v[44:45], v[220:221]
	v_pk_add_f32 v[46:47], v[46:47], v[222:223]
	global_load_dwordx4 v[220:223], v80, s[86:87]
	s_add_u32 s86, s86, 0x2000
	s_addc_u32 s87, s87, 0
	s_waitcnt vmcnt(15)
	v_pk_add_f32 v[48:49], v[48:49], v[224:225]
	v_pk_add_f32 v[50:51], v[50:51], v[226:227]
	global_load_dwordx4 v[224:227], v80, s[86:87]
	s_add_u32 s86, s86, 0x2000
	s_addc_u32 s87, s87, 0
	s_waitcnt vmcnt(15)
	v_pk_add_f32 v[52:53], v[52:53], v[84:85]
	v_pk_add_f32 v[54:55], v[54:55], v[86:87]
	global_load_dwordx4 v[84:87], v80, s[86:87]
	s_add_u32 s86, s86, 0x2000
	s_addc_u32 s87, s87, 0
	s_waitcnt vmcnt(15)
	v_pk_add_f32 v[56:57], v[56:57], v[88:89]
	v_pk_add_f32 v[58:59], v[58:59], v[90:91]
	global_load_dwordx4 v[88:91], v80, s[86:87]
	s_add_u32 s86, s86, 0x2000
	s_addc_u32 s87, s87, 0
	s_waitcnt vmcnt(15)
	v_pk_add_f32 v[60:61], v[60:61], v[92:93]
	v_pk_add_f32 v[62:63], v[62:63], v[94:95]
	global_load_dwordx4 v[92:95], v80, s[86:87]
	s_add_u32 s86, s86, 0x2000
	s_addc_u32 s87, s87, 0
	s_waitcnt vmcnt(15)
	v_pk_add_f32 v[64:65], v[64:65], v[170:171]
	v_pk_add_f32 v[66:67], v[66:67], v[172:173]
	s_waitcnt vmcnt(14)
	v_pk_add_f32 v[68:69], v[68:69], v[174:175]
	v_pk_add_f32 v[70:71], v[70:71], v[176:177]
	s_waitcnt vmcnt(13)
	v_pk_add_f32 v[72:73], v[72:73], v[178:179]
	v_pk_add_f32 v[74:75], v[74:75], v[180:181]
	s_waitcnt vmcnt(12)
	v_pk_add_f32 v[76:77], v[76:77], v[182:183]
	v_pk_add_f32 v[78:79], v[78:79], v[184:185]
	s_waitcnt vmcnt(11)
	v_pk_add_f32 v[96:97], v[96:97], v[186:187]
	v_pk_add_f32 v[98:99], v[98:99], v[188:189]
	s_waitcnt vmcnt(10)
	v_pk_add_f32 v[100:101], v[100:101], v[190:191]
	v_pk_add_f32 v[102:103], v[102:103], v[192:193]
	s_waitcnt vmcnt(9)
	v_pk_add_f32 v[104:105], v[104:105], v[194:195]
	v_pk_add_f32 v[106:107], v[106:107], v[196:197]
	s_waitcnt vmcnt(8)
	v_pk_add_f32 v[108:109], v[108:109], v[198:199]
	v_pk_add_f32 v[110:111], v[110:111], v[200:201]
	s_waitcnt vmcnt(7)
	v_pk_add_f32 v[112:113], v[112:113], v[202:203]
	v_pk_add_f32 v[114:115], v[114:115], v[204:205]
	s_waitcnt vmcnt(6)
	v_pk_add_f32 v[116:117], v[116:117], v[206:207]
	v_pk_add_f32 v[118:119], v[118:119], v[208:209]
	s_waitcnt vmcnt(5)
	v_pk_add_f32 v[120:121], v[120:121], v[216:217]
	v_pk_add_f32 v[122:123], v[122:123], v[218:219]
	s_waitcnt vmcnt(4)
	v_pk_add_f32 v[124:125], v[124:125], v[220:221]
	v_pk_add_f32 v[126:127], v[126:127], v[222:223]
	s_waitcnt vmcnt(3)
	v_pk_add_f32 v[128:129], v[128:129], v[224:225]
	v_pk_add_f32 v[130:131], v[130:131], v[226:227]
	s_waitcnt vmcnt(2)
	v_pk_add_f32 v[132:133], v[132:133], v[84:85]
	v_pk_add_f32 v[134:135], v[134:135], v[86:87]
	s_waitcnt vmcnt(1)
	v_pk_add_f32 v[136:137], v[136:137], v[88:89]
	v_pk_add_f32 v[138:139], v[138:139], v[90:91]
	s_waitcnt vmcnt(0)
	v_pk_add_f32 v[140:141], v[140:141], v[92:93]
	v_pk_add_f32 v[142:143], v[142:143], v[94:95]
